# drain wait before an item's first loads leaves the newest op (the queue-prefetch atomic) outstanding: vmcnt(1) instead of vmcnt(0)
# speedup vs baseline: 1.0027x; 1.0016x over previous
; __device__ __forceinline__ void item_conv(const Params& p, int l, int item) {
;   const float* cw = p.conv_w + l * 3 * 512;
;   for (int e = threadIdx.x; e < 128 * 64; e += NTHR) {
;     int tok = item * 128 + (e >> 6), c = (e & 63) * 8;
;     int t, b; bool samp = tok >= NP;
;     if (!samp) { t = tok & 2047; b = tok >> 11; } else { int ts = tok - NP; t = ts & 15; b = ts >> 4; }
;     float y[8];
; #pragma unroll
;     for (int i = 0; i < 8; ++i) y[i] = 0.f;
; #pragma unroll
;     for (int j = 0; j < 3; ++j) {
;       int pi = t + j;
;       float f[8];
;       if (pi >= 2) {
;         uint4 raw = *reinterpret_cast<const uint4*>(p.u + (long)(tok - 2 + j) * 512 + c);
;         unsigned w[4] = {raw.x, raw.y, raw.z, raw.w};
; #pragma unroll
;         for (int i = 0; i < 4; ++i) { f[2 * i] = __uint_as_float(w[i] << 16); f[2 * i + 1] = __uint_as_float(w[i] & 0xffff0000u); }
;       } else if (samp) {
;         const float* ps = p.cconv + ((long)(l * 16 + b) * 2 + pi) * 512 + c;
; #pragma unroll
;         for (int i = 0; i < 8; ++i) f[i] = ps[i];
;       } else {
; #pragma unroll
;         for (int i = 0; i < 8; ++i) f[i] = 0.f;
;       }
; #pragma unroll
;       for (int i = 0; i < 8; ++i) y[i] += f[i] * cw[j * 512 + c + i];
.LBB0_487:
	s_waitcnt vmcnt(1)
	v_readlane_b32 s28, v246, 25
	v_readlane_b32 s29, v246, 26
	v_readlane_b32 s26, v246, 16
	v_readlane_b32 s4, v248, 59
	v_readlane_b32 s5, v248, 60
	v_readlane_b32 s6, v248, 63
	v_readlane_b32 s7, v247, 0
	v_readlane_b32 s8, v248, 24
	v_readlane_b32 s9, v248, 25
	v_and_b32_e32 v249, 63, v188
	v_lshlrev_b32_e32 v251, 5, v249
	v_lshlrev_b32_e32 v249, 4, v249
	v_lshlrev_b32_e32 v250, 4, v188
	v_readfirstlane_b32 s10, v210
	s_add_u32 s12, s28, 0x1000
	s_addc_u32 s13, s29, 0
	global_load_dwordx4 v[0:3], v251, s[28:29]
	global_load_dwordx4 v[4:7], v251, s[28:29] offset:16
	global_load_dwordx4 v[8:11], v251, s[28:29] offset:2048
	global_load_dwordx4 v[12:15], v251, s[28:29] offset:2064
	global_load_dwordx4 v[16:19], v251, s[12:13]
	global_load_dwordx4 v[20:23], v251, s[12:13] offset:16
	s_lshl_b32 s11, s46, 7
	s_add_i32 s10, s10, s11
	s_mov_b32 s11, 0
	s_cmp_gt_u32 s10, 0xffff
	s_cselect_b32 s13, 1, 0
	s_waitcnt vmcnt(0)
	ds_write_b128 v250, v[0:3]
	ds_write_b128 v250, v[4:7] offset:8192
	ds_write_b128 v250, v[8:11] offset:16384
	ds_write_b128 v250, v[12:15] offset:24576
	ds_write_b128 v250, v[16:19] offset:32768
	ds_write_b128 v250, v[20:23] offset:40960
	s_waitcnt lgkmcnt(0)

; __device__ __forceinline__ int otid() { int t = threadIdx.x; asm volatile("" : "+v"(t)); return t; }
; __device__ __forceinline__ void item_attn(const Params& p, int l, int aidx) {
;   const int tid = otid(), wid = __builtin_amdgcn_readfirstlane(tid >> 6), lane = tid & 63, fr = lane & 15, fq = lane >> 4;
;   const bool samp = aidx >= 2048;
;   int b, hd, nq, qpos0, ntiles; long tokq0;
;   const float *kbase, *vbase, *kcache = nullptr, *vcache = nullptr;
;   if (!samp) {
;     int qb = 7 - (aidx >> 8); int r = aidx & 255; b = r >> 3; hd = r & 7;
;     nq = 256; qpos0 = qb * 256; tokq0 = (long)b * 2048 + qpos0; ntiles = qb * 4 + 4;
;     kbase = p.out + OFF_KP + ((long)l * 65536 + (long)b * 2048) * 512 + hd * 64;
;     vbase = p.out + OFF_VP + ((long)l * 65536 + (long)b * 2048) * 512 + hd * 64;
;   } else {
;     int r = aidx - 2048; b = r >> 3; hd = r & 7;
;     nq = 16; qpos0 = 1024; tokq0 = NP + (long)b * 16; ntiles = 17;
;     kbase = p.out + OFF_KS + ((long)l * 256 + (long)b * 16) * 512 + hd * 64;
;     vbase = p.out + OFF_VS + ((long)l * 256 + (long)b * 16) * 512 + hd * 64;
;     kcache = p.ck + ((long)(l * 16 + b) * 1024) * 512 + hd * 64;
;     vcache = p.cv + ((long)(l * 16 + b) * 1024) * 512 + hd * 64;
;   }
;   u16* Ks = reinterpret_cast<u16*>(smem + AKS);
;   u16* VT = reinterpret_cast<u16*>(smem + AVT);
;   bf16x8 qf[2][2];
;   bool rowv[2];
; #pragma unroll
;   for (int n = 0; n < 2; ++n) {
;     int row = 32 * wid + 16 * n + fr;
;     rowv[n] = row < nq;
; #pragma unroll
;     for (int ks = 0; ks < 2; ++ks) {
;       bf16x8 z = {0, 0, 0, 0, 0, 0, 0, 0};
;       if (rowv[n]) z = *reinterpret_cast<const bf16x8*>(p.sq + (tokq0 + row) * 512 + hd * 64 + ks * 32 + fq * 8);
;       qf[n][ks] = z;
;     }
;   }
.LBB0_509:
	v_xor_b32_e32 v241, 16, v215
	v_xor_b32_e32 v242, 32, v215
	v_xor_b32_e32 v243, 48, v215
	v_lshlrev_b32_e32 v241, 2, v241
	v_lshlrev_b32_e32 v242, 2, v242
	v_lshlrev_b32_e32 v243, 2, v243
	s_ashr_i32 s2, s2, 6
	v_and_b32_e32 v33, 15, v32
	s_lshl_b32 s21, s2, 5
	v_readlane_b32 s48, v247, 7
	v_or_b32_e32 v84, s21, v33
	s_lshl_b64 s[44:45], s[28:29], 1
	v_readlane_b32 s52, v247, 11
	v_readlane_b32 s53, v247, 12
	s_add_u32 s0, s52, s44
	v_ashrrev_i32_e32 v85, 31, v84
	s_addc_u32 s1, s53, s45
	v_and_b32_e32 v190, 48, v32
	v_lshl_add_u64 v[0:1], s[34:35], 0, v[84:85]
	v_lshl_add_u64 v[8:9], s[0:1], 0, v[190:191]
	v_lshlrev_b64 v[82:83], 10, v[0:1]
	v_cmp_gt_i32_e64 s[8:9], s47, v84
	v_lshl_add_u64 v[10:11], v[8:9], 0, v[82:83]
	v_mov_b32_e32 v0, 0
	v_mov_b32_e32 v4, 0
	v_mov_b32_e32 v5, 0
	v_mov_b32_e32 v6, 0
	v_mov_b32_e32 v7, 0
	v_readlane_b32 s49, v247, 8
	v_readlane_b32 s50, v247, 9
	v_readlane_b32 s51, v247, 10
	v_readlane_b32 s54, v247, 13
	v_readlane_b32 s55, v247, 14
	v_readlane_b32 s56, v247, 15
	v_readlane_b32 s57, v247, 16
	v_readlane_b32 s58, v247, 17
	v_readlane_b32 s59, v247, 18
	v_readlane_b32 s60, v247, 19
	v_readlane_b32 s61, v247, 20
	v_readlane_b32 s62, v247, 21
	v_readlane_b32 s63, v247, 22
	s_waitcnt vmcnt(1)
	s_and_saveexec_b64 s[0:1], s[8:9]
	s_cbranch_execz .LBB0_511
	global_load_dwordx4 v[4:7], v[10:11], off
